# P3: c1/c2 column sums moved from workgroups 0..10 (ahead of their scan chains) to idle workgroups 64..74
# baseline (speedup 1.0000x reference)
; __device__ __forceinline__ int lbid() { int b = blockIdx.x; asm volatile("" : "+s"(b)); return b; }
; __device__ __forceinline__ int lgdim() { int g = gridDim.x; asm volatile("" : "+s"(g)); return g; }
; DI void chunk_scans(const Args& a, int tid) {
;     const int gt = lbid() * 512 + tid, NT = lgdim() * 512;
;     for (int n = gt; n < 2 * DFF; n += NT) { const float* p1 = (const float*)(a.ws + WS_W + W_PART1) + n; const float* p2 = (const float*)(a.ws + WS_W + W_PART2) + n; float s1 = 0.f, s2 = 0.f;
; #pragma unroll
;         for (int kb = 0; kb < 16; ++kb) { s1 += p1[(size_t)kb * 2 * DFF]; s2 += p2[(size_t)kb * 2 * DFF]; }
;         ((float*)(a.ws + WS_W + W_C1F))[n] = s1; ((float*)(a.ws + WS_W + W_C2F))[n] = s2; }
.LBB0_1233:
	s_or_b64 exec, exec, s[16:17]
	v_readlane_b32 s2, v254, 2
	v_readlane_b32 s3, v254, 3
	s_waitcnt lgkmcnt(0)
	s_barrier
	s_load_dwordx4 s[16:19], s[2:3], 0xf0
	s_mov_b32 s2, s77
	v_mbcnt_lo_u32_b32 v0, -1, 0
	v_mbcnt_hi_u32_b32 v0, -1, v0
	s_nop 0
	v_lshl_or_b32 v0, s2, 6, v0
	s_mov_b32 s2, s87
	s_nop 0
	v_readlane_b32 s2, v254, 0
	s_mov_b32 s12, s2
	s_mov_b32 s2, s87
	v_readlane_b32 s3, v254, 1
	s_lshl_b32 s7, s2, 9
	v_add_u32_e32 v2, s7, v0
	s_mov_b32 s3, s12
	s_movk_i32 s12, 0x1600
	s_lshl_b32 s20, s3, 9
	v_subrev_u32_e32 v2, 0x8000, v2
	v_cmp_gt_u32_e32 vcc, s12, v2
	s_and_saveexec_b64 s[22:23], vcc
	s_cbranch_execz .LBB0_1236
	v_ashrrev_i32_e32 v3, 31, v2
	s_waitcnt lgkmcnt(0)
	v_lshl_add_u64 v[4:5], v[2:3], 2, s[18:19]
	s_mov_b64 s[12:13], 0x1a00000
	s_ashr_i32 s21, s20, 31
	v_lshl_add_u64 v[4:5], v[4:5], 0, s[12:13]
	s_lshl_b64 s[24:25], s[20:21], 2
	s_mov_b64 s[26:27], 0
	v_mov_b32_e32 v3, v2

; DI unsigned pk2(float lo, float hi) { const f32x2 v = {lo, hi}; const hwbf16x2 b = __builtin_convertvector(v, hwbf16x2); return __builtin_bit_cast(unsigned, b); }
; DI f32x4 bf4_to_f32(const u32x2 v) { return (f32x4){__uint_as_float(v.x << 16), __uint_as_float(v.x & 0xffff0000u), __uint_as_float(v.y << 16), __uint_as_float(v.y & 0xffff0000u)}; }
; DI float ret_lg(int h) { return log1pf(-exp2f(-5.0f - (float)h)); }
; DI void chunk_scans(const Args& a, int tid) {
;     ...
;     for (int idx = gt; idx < 16384 + 8192 + 512; idx += NT) {
;         if (idx < 16384) { const int b = idx >> 13, rem = (idx & 8191) * 4, h = rem >> 13;
;             bf16_t* p = (bf16_t*)((unsigned char*)a.out + DO_ST) + (size_t)b * NCH * 32768 + rem; const float* dec = (const float*)(a.ws + WS_SDEC) + b * NCH * 4 + h; f32x4 st = {0.f, 0.f, 0.f, 0.f};
; #pragma unroll 1
;             for (int c0 = 0; c0 < NCH; c0 += 16) { u32x2 t[16]; float d[16];
; #pragma unroll
;                 for (int j = 0; j < 16; ++j) { t[j] = *(const u32x2*)(p + (size_t)(c0 + j) * 32768); d[j] = dec[(c0 + j) * 4]; }
; #pragma unroll
;                 for (int j = 0; j < 16; ++j) { u32x2 w; w.x = pk2(st[0], st[1]); w.y = pk2(st[2], st[3]); *(u32x2*)(p + (size_t)(c0 + j) * 32768) = w; st = st * d[j] + bf4_to_f32(t[j]); } }
;         } else if (idx < 16384 + 8192) { const int i2 = idx - 16384, b = i2 >> 12, rem = (i2 & 4095) * 4, h = rem >> 12; const float cd = __expf(ret_lg(h) * 128.0f);
;             bf16_t* p = (bf16_t*)((unsigned char*)a.out + DO_RS) + (size_t)b * NCH * 16384 + rem; f32x4 st = {0.f, 0.f, 0.f, 0.f};
.LBB0_1236:
	s_or_b64 exec, exec, s[22:23]
	v_add_u32_e32 v2, 0x8000, v2
	s_movk_i32 s12, 0x6200
	v_cmp_gt_i32_e32 vcc, s12, v2
	s_and_saveexec_b64 s[22:23], vcc
	s_cbranch_execz .LBB0_1250
	s_waitcnt lgkmcnt(0)
	s_add_u32 s24, s16, 0x5000000
	v_add_u32_e32 v5, s7, v0
	s_addc_u32 s25, s17, 0
	s_lshl_b32 s7, s3, 11
	s_add_u32 s26, s18, 0x26800f0
	v_mov_b32_e32 v3, 2
	v_mov_b32_e32 v6, 3
	s_addc_u32 s27, s19, 0
	v_lshlrev_b32_sdwa v4, v3, v0 dst_sel:DWORD dst_unused:UNUSED_PAD src0_sel:DWORD src1_sel:BYTE_0
	v_lshlrev_b32_sdwa v6, v6, v0 dst_sel:DWORD dst_unused:UNUSED_PAD src0_sel:DWORD src1_sel:BYTE_0
	v_lshlrev_b32_e32 v0, 2, v0
	s_add_u32 s16, s16, 0x30f0000
	v_add_u32_e32 v3, 0xffffa000, v5
	v_add_u32_e32 v5, 0xffffc000, v5
	v_lshl_add_u32 v7, s2, 11, v0
	s_addc_u32 s17, s17, 0
	s_mov_b64 s[36:37], 0
	s_branch .LBB0_1239
